# KV-cache conversion units double-buffered (next pair of rows in flight while one pair is converted and stored)
# speedup vs baseline: 1.0032x; 1.0012x over previous
.LBB0_850:
	s_addk_i32 s7, 0xff00
	s_lshr_b32 s7, s7, 1
	s_andn2_b64 vcc, exec, s[40:41]
	s_mov_b64 s[38:39], -1
	s_cbranch_vccnz .LBB0_857
	v_mov_b32_e32 v2, v0
	s_lshl_b32 s10, s7, 7
	v_readfirstlane_b32 s9, v2
	s_ashr_i32 s9, s9, 2
	s_and_b32 s9, s9, -16
	s_add_i32 s9, s9, s10
	s_cmpk_lt_u32 s9, 0x8000
	s_cselect_b32 s10, 16, 24
	s_add_u32 s10, s80, s10
	s_addc_u32 s11, s81, 0
	s_lshr_b32 s12, s9, 15
	s_bfe_u32 s13, s9, 0x4000b
	s_load_dwordx2 s[10:11], s[10:11], 0x0
	s_mul_i32 s12, s12, 0x8400000
	s_mul_i32 s13, s13, 0x840000
	s_add_i32 s12, s12, s13
	s_lshl_b32 s13, s9, 12
	s_and_b32 s13, s13, 0x7f0000
	s_add_i32 s12, s13, s12
	s_lshl_b32 s9, s9, 13
	s_add_i32 s12, s12, 0x10000
	s_and_b32 s9, s9, 0xffe0000
	v_and_b32_e32 v3, 63, v2
	s_waitcnt lgkmcnt(0)
	s_add_u32 s10, s10, s9
	v_lshlrev_b32_e32 v66, 5, v3
	s_addc_u32 s11, s11, 0
	v_lshl_or_b32 v36, v3, 4, s12
	v_lshl_add_u64 v[2:3], s[10:11], 0, v[66:67]
	s_mov_b64 s[10:11], 0x3810
	v_lshl_add_u64 v[34:35], v[2:3], 0, s[10:11]
	s_mov_b32 s9, -2
	s_mov_b32 s10, 0xffffd7f0
	s_mov_b32 s11, -1
	v_lshl_add_u64 v[2:3], v[34:35], 0, s[10:11]
	s_mov_b32 s10, 0xfffff7f0
	v_lshl_add_u64 v[4:5], v[34:35], 0, s[10:11]
	s_mov_b64 s[10:11], 0x4000
	v_add_u32_e32 v37, 0x1000, v36
	global_load_dwordx4 v[68:71], v[2:3], off offset:-4096
	global_load_dwordx4 v[72:75], v[2:3], off offset:-4080
	global_load_dwordx4 v[76:79], v[2:3], off offset:-2048
	global_load_dwordx4 v[80:83], v[2:3], off offset:-2032
	global_load_dwordx4 v[84:87], v[2:3], off
	global_load_dwordx4 v[88:91], v[2:3], off offset:16
	global_load_dwordx4 v[92:95], v[2:3], off offset:2048
	global_load_dwordx4 v[96:99], v[2:3], off offset:2064
	global_load_dwordx4 v[100:103], v[4:5], off offset:-4096
	global_load_dwordx4 v[104:107], v[4:5], off offset:-4080
	global_load_dwordx4 v[108:111], v[4:5], off offset:-2048
	global_load_dwordx4 v[112:115], v[4:5], off offset:-2032
	global_load_dwordx4 v[116:119], v[4:5], off
	global_load_dwordx4 v[120:123], v[4:5], off offset:16
	global_load_dwordx4 v[124:127], v[4:5], off offset:2048
	global_load_dwordx4 v[128:131], v[4:5], off offset:2064
	v_lshl_add_u64 v[2:3], v[2:3], 0, s[10:11]
	v_lshl_add_u64 v[4:5], v[4:5], 0, s[10:11]
	global_load_dwordx4 v[132:135], v[2:3], off offset:-4096
	global_load_dwordx4 v[136:139], v[2:3], off offset:-4080
	global_load_dwordx4 v[140:143], v[2:3], off offset:-2048
	global_load_dwordx4 v[144:147], v[2:3], off offset:-2032
	global_load_dwordx4 v[148:151], v[2:3], off
	global_load_dwordx4 v[152:155], v[2:3], off offset:16
	global_load_dwordx4 v[156:159], v[2:3], off offset:2048
	global_load_dwordx4 v[160:163], v[2:3], off offset:2064
	global_load_dwordx4 v[164:167], v[4:5], off offset:-4096
	global_load_dwordx4 v[168:171], v[4:5], off offset:-4080
	global_load_dwordx4 v[172:175], v[4:5], off offset:-2048
	global_load_dwordx4 v[176:179], v[4:5], off offset:-2032
	global_load_dwordx4 v[180:183], v[4:5], off
	global_load_dwordx4 v[184:187], v[4:5], off offset:16
	global_load_dwordx4 v[188:191], v[4:5], off offset:2048
	global_load_dwordx4 v[192:195], v[4:5], off offset:2064
	v_lshl_add_u64 v[2:3], v[2:3], 0, s[10:11]
	v_lshl_add_u64 v[4:5], v[4:5], 0, s[10:11]
	s_waitcnt vmcnt(16)
	v_cvt_pk_bf16_f32 v68, v68, v69
	v_cvt_pk_bf16_f32 v69, v70, v71
	v_cvt_pk_bf16_f32 v70, v72, v73
	v_cvt_pk_bf16_f32 v71, v74, v75
	buffer_store_dwordx4 v[68:71], v36, s[84:87], 0 offen sc1
	v_cvt_pk_bf16_f32 v76, v76, v77
	v_cvt_pk_bf16_f32 v77, v78, v79
	v_cvt_pk_bf16_f32 v78, v80, v81
	v_cvt_pk_bf16_f32 v79, v82, v83
	buffer_store_dwordx4 v[76:79], v36, s[84:87], 0 offen offset:1024 sc1
	v_cvt_pk_bf16_f32 v84, v84, v85
	v_cvt_pk_bf16_f32 v85, v86, v87
	v_cvt_pk_bf16_f32 v86, v88, v89
	v_cvt_pk_bf16_f32 v87, v90, v91
	buffer_store_dwordx4 v[84:87], v36, s[84:87], 0 offen offset:2048 sc1
	v_cvt_pk_bf16_f32 v92, v92, v93
	v_cvt_pk_bf16_f32 v93, v94, v95
	v_cvt_pk_bf16_f32 v94, v96, v97
	v_cvt_pk_bf16_f32 v95, v98, v99
	buffer_store_dwordx4 v[92:95], v36, s[84:87], 0 offen offset:3072 sc1
	v_cvt_pk_bf16_f32 v100, v100, v101
	v_cvt_pk_bf16_f32 v101, v102, v103
	v_cvt_pk_bf16_f32 v102, v104, v105
	v_cvt_pk_bf16_f32 v103, v106, v107
	buffer_store_dwordx4 v[100:103], v37, s[84:87], 0 offen sc1
	v_cvt_pk_bf16_f32 v108, v108, v109
	v_cvt_pk_bf16_f32 v109, v110, v111
	v_cvt_pk_bf16_f32 v110, v112, v113
	v_cvt_pk_bf16_f32 v111, v114, v115
	buffer_store_dwordx4 v[108:111], v37, s[84:87], 0 offen offset:1024 sc1
	v_cvt_pk_bf16_f32 v116, v116, v117
	v_cvt_pk_bf16_f32 v117, v118, v119
	v_cvt_pk_bf16_f32 v118, v120, v121
	v_cvt_pk_bf16_f32 v119, v122, v123
	buffer_store_dwordx4 v[116:119], v37, s[84:87], 0 offen offset:2048 sc1
	v_cvt_pk_bf16_f32 v124, v124, v125
	v_cvt_pk_bf16_f32 v125, v126, v127
	v_cvt_pk_bf16_f32 v126, v128, v129
	v_cvt_pk_bf16_f32 v127, v130, v131
	buffer_store_dwordx4 v[124:127], v37, s[84:87], 0 offen offset:3072 sc1
	v_add_u32_e32 v36, 0x2000, v36
	v_add_u32_e32 v37, 0x2000, v37
	global_load_dwordx4 v[68:71], v[2:3], off offset:-4096
	global_load_dwordx4 v[72:75], v[2:3], off offset:-4080
	global_load_dwordx4 v[76:79], v[2:3], off offset:-2048
	global_load_dwordx4 v[80:83], v[2:3], off offset:-2032
	global_load_dwordx4 v[84:87], v[2:3], off
	global_load_dwordx4 v[88:91], v[2:3], off offset:16
	global_load_dwordx4 v[92:95], v[2:3], off offset:2048
	global_load_dwordx4 v[96:99], v[2:3], off offset:2064
	global_load_dwordx4 v[100:103], v[4:5], off offset:-4096
	global_load_dwordx4 v[104:107], v[4:5], off offset:-4080
	global_load_dwordx4 v[108:111], v[4:5], off offset:-2048
	global_load_dwordx4 v[112:115], v[4:5], off offset:-2032
	global_load_dwordx4 v[116:119], v[4:5], off
	global_load_dwordx4 v[120:123], v[4:5], off offset:16
	global_load_dwordx4 v[124:127], v[4:5], off offset:2048
	global_load_dwordx4 v[128:131], v[4:5], off offset:2064
	v_lshl_add_u64 v[2:3], v[2:3], 0, s[10:11]
	v_lshl_add_u64 v[4:5], v[4:5], 0, s[10:11]
	s_waitcnt vmcnt(24)
	v_cvt_pk_bf16_f32 v132, v132, v133
	v_cvt_pk_bf16_f32 v133, v134, v135
	v_cvt_pk_bf16_f32 v134, v136, v137
	v_cvt_pk_bf16_f32 v135, v138, v139
	buffer_store_dwordx4 v[132:135], v36, s[84:87], 0 offen sc1
	v_cvt_pk_bf16_f32 v140, v140, v141
	v_cvt_pk_bf16_f32 v141, v142, v143
	v_cvt_pk_bf16_f32 v142, v144, v145
	v_cvt_pk_bf16_f32 v143, v146, v147
	buffer_store_dwordx4 v[140:143], v36, s[84:87], 0 offen offset:1024 sc1
	v_cvt_pk_bf16_f32 v148, v148, v149
	v_cvt_pk_bf16_f32 v149, v150, v151
	v_cvt_pk_bf16_f32 v150, v152, v153
	v_cvt_pk_bf16_f32 v151, v154, v155
	buffer_store_dwordx4 v[148:151], v36, s[84:87], 0 offen offset:2048 sc1
	v_cvt_pk_bf16_f32 v156, v156, v157
	v_cvt_pk_bf16_f32 v157, v158, v159
	v_cvt_pk_bf16_f32 v158, v160, v161
	v_cvt_pk_bf16_f32 v159, v162, v163
	buffer_store_dwordx4 v[156:159], v36, s[84:87], 0 offen offset:3072 sc1
	v_cvt_pk_bf16_f32 v164, v164, v165
	v_cvt_pk_bf16_f32 v165, v166, v167
	v_cvt_pk_bf16_f32 v166, v168, v169
	v_cvt_pk_bf16_f32 v167, v170, v171
	buffer_store_dwordx4 v[164:167], v37, s[84:87], 0 offen sc1
	v_cvt_pk_bf16_f32 v172, v172, v173
	v_cvt_pk_bf16_f32 v173, v174, v175
	v_cvt_pk_bf16_f32 v174, v176, v177
	v_cvt_pk_bf16_f32 v175, v178, v179
	buffer_store_dwordx4 v[172:175], v37, s[84:87], 0 offen offset:1024 sc1
	v_cvt_pk_bf16_f32 v180, v180, v181
	v_cvt_pk_bf16_f32 v181, v182, v183
	v_cvt_pk_bf16_f32 v182, v184, v185
	v_cvt_pk_bf16_f32 v183, v186, v187
	buffer_store_dwordx4 v[180:183], v37, s[84:87], 0 offen offset:2048 sc1
	v_cvt_pk_bf16_f32 v188, v188, v189
	v_cvt_pk_bf16_f32 v189, v190, v191
	v_cvt_pk_bf16_f32 v190, v192, v193
	v_cvt_pk_bf16_f32 v191, v194, v195
	buffer_store_dwordx4 v[188:191], v37, s[84:87], 0 offen offset:3072 sc1
	v_add_u32_e32 v36, 0x2000, v36
	v_add_u32_e32 v37, 0x2000, v37
	global_load_dwordx4 v[132:135], v[2:3], off offset:-4096
	global_load_dwordx4 v[136:139], v[2:3], off offset:-4080
	global_load_dwordx4 v[140:143], v[2:3], off offset:-2048
	global_load_dwordx4 v[144:147], v[2:3], off offset:-2032
	global_load_dwordx4 v[148:151], v[2:3], off
	global_load_dwordx4 v[152:155], v[2:3], off offset:16
	global_load_dwordx4 v[156:159], v[2:3], off offset:2048
	global_load_dwordx4 v[160:163], v[2:3], off offset:2064
	global_load_dwordx4 v[164:167], v[4:5], off offset:-4096
	global_load_dwordx4 v[168:171], v[4:5], off offset:-4080
	global_load_dwordx4 v[172:175], v[4:5], off offset:-2048
	global_load_dwordx4 v[176:179], v[4:5], off offset:-2032
	global_load_dwordx4 v[180:183], v[4:5], off
	global_load_dwordx4 v[184:187], v[4:5], off offset:16
	global_load_dwordx4 v[188:191], v[4:5], off offset:2048
	global_load_dwordx4 v[192:195], v[4:5], off offset:2064
	v_lshl_add_u64 v[2:3], v[2:3], 0, s[10:11]
	v_lshl_add_u64 v[4:5], v[4:5], 0, s[10:11]
	s_waitcnt vmcnt(24)
	v_cvt_pk_bf16_f32 v68, v68, v69
	v_cvt_pk_bf16_f32 v69, v70, v71
	v_cvt_pk_bf16_f32 v70, v72, v73
	v_cvt_pk_bf16_f32 v71, v74, v75
	buffer_store_dwordx4 v[68:71], v36, s[84:87], 0 offen sc1
	v_cvt_pk_bf16_f32 v76, v76, v77
	v_cvt_pk_bf16_f32 v77, v78, v79
	v_cvt_pk_bf16_f32 v78, v80, v81
	v_cvt_pk_bf16_f32 v79, v82, v83
	buffer_store_dwordx4 v[76:79], v36, s[84:87], 0 offen offset:1024 sc1
	v_cvt_pk_bf16_f32 v84, v84, v85
	v_cvt_pk_bf16_f32 v85, v86, v87
	v_cvt_pk_bf16_f32 v86, v88, v89
	v_cvt_pk_bf16_f32 v87, v90, v91
	buffer_store_dwordx4 v[84:87], v36, s[84:87], 0 offen offset:2048 sc1
	v_cvt_pk_bf16_f32 v92, v92, v93
	v_cvt_pk_bf16_f32 v93, v94, v95
	v_cvt_pk_bf16_f32 v94, v96, v97
	v_cvt_pk_bf16_f32 v95, v98, v99
	buffer_store_dwordx4 v[92:95], v36, s[84:87], 0 offen offset:3072 sc1
	v_cvt_pk_bf16_f32 v100, v100, v101
	v_cvt_pk_bf16_f32 v101, v102, v103
	v_cvt_pk_bf16_f32 v102, v104, v105
	v_cvt_pk_bf16_f32 v103, v106, v107
	buffer_store_dwordx4 v[100:103], v37, s[84:87], 0 offen sc1
	v_cvt_pk_bf16_f32 v108, v108, v109
	v_cvt_pk_bf16_f32 v109, v110, v111
	v_cvt_pk_bf16_f32 v110, v112, v113
	v_cvt_pk_bf16_f32 v111, v114, v115
	buffer_store_dwordx4 v[108:111], v37, s[84:87], 0 offen offset:1024 sc1
	v_cvt_pk_bf16_f32 v116, v116, v117
	v_cvt_pk_bf16_f32 v117, v118, v119
	v_cvt_pk_bf16_f32 v118, v120, v121
	v_cvt_pk_bf16_f32 v119, v122, v123
	buffer_store_dwordx4 v[116:119], v37, s[84:87], 0 offen offset:2048 sc1
	v_cvt_pk_bf16_f32 v124, v124, v125
	v_cvt_pk_bf16_f32 v125, v126, v127
	v_cvt_pk_bf16_f32 v126, v128, v129
	v_cvt_pk_bf16_f32 v127, v130, v131
	buffer_store_dwordx4 v[124:127], v37, s[84:87], 0 offen offset:3072 sc1
	v_add_u32_e32 v36, 0x2000, v36
	v_add_u32_e32 v37, 0x2000, v37
	global_load_dwordx4 v[68:71], v[2:3], off offset:-4096
	global_load_dwordx4 v[72:75], v[2:3], off offset:-4080
	global_load_dwordx4 v[76:79], v[2:3], off offset:-2048
	global_load_dwordx4 v[80:83], v[2:3], off offset:-2032
	global_load_dwordx4 v[84:87], v[2:3], off
	global_load_dwordx4 v[88:91], v[2:3], off offset:16
	global_load_dwordx4 v[92:95], v[2:3], off offset:2048
	global_load_dwordx4 v[96:99], v[2:3], off offset:2064
	global_load_dwordx4 v[100:103], v[4:5], off offset:-4096
	global_load_dwordx4 v[104:107], v[4:5], off offset:-4080
	global_load_dwordx4 v[108:111], v[4:5], off offset:-2048
	global_load_dwordx4 v[112:115], v[4:5], off offset:-2032
	global_load_dwordx4 v[116:119], v[4:5], off
	global_load_dwordx4 v[120:123], v[4:5], off offset:16
	global_load_dwordx4 v[124:127], v[4:5], off offset:2048
	global_load_dwordx4 v[128:131], v[4:5], off offset:2064
	v_lshl_add_u64 v[2:3], v[2:3], 0, s[10:11]
	v_lshl_add_u64 v[4:5], v[4:5], 0, s[10:11]
	s_waitcnt vmcnt(24)
	v_cvt_pk_bf16_f32 v132, v132, v133
	v_cvt_pk_bf16_f32 v133, v134, v135
	v_cvt_pk_bf16_f32 v134, v136, v137
	v_cvt_pk_bf16_f32 v135, v138, v139
	buffer_store_dwordx4 v[132:135], v36, s[84:87], 0 offen sc1
	v_cvt_pk_bf16_f32 v140, v140, v141
	v_cvt_pk_bf16_f32 v141, v142, v143
	v_cvt_pk_bf16_f32 v142, v144, v145
	v_cvt_pk_bf16_f32 v143, v146, v147
	buffer_store_dwordx4 v[140:143], v36, s[84:87], 0 offen offset:1024 sc1
	v_cvt_pk_bf16_f32 v148, v148, v149
	v_cvt_pk_bf16_f32 v149, v150, v151
	v_cvt_pk_bf16_f32 v150, v152, v153
	v_cvt_pk_bf16_f32 v151, v154, v155
	buffer_store_dwordx4 v[148:151], v36, s[84:87], 0 offen offset:2048 sc1
	v_cvt_pk_bf16_f32 v156, v156, v157
	v_cvt_pk_bf16_f32 v157, v158, v159
	v_cvt_pk_bf16_f32 v158, v160, v161
	v_cvt_pk_bf16_f32 v159, v162, v163
	buffer_store_dwordx4 v[156:159], v36, s[84:87], 0 offen offset:3072 sc1
	v_cvt_pk_bf16_f32 v164, v164, v165
	v_cvt_pk_bf16_f32 v165, v166, v167
	v_cvt_pk_bf16_f32 v166, v168, v169
	v_cvt_pk_bf16_f32 v167, v170, v171
	buffer_store_dwordx4 v[164:167], v37, s[84:87], 0 offen sc1
	v_cvt_pk_bf16_f32 v172, v172, v173
	v_cvt_pk_bf16_f32 v173, v174, v175
	v_cvt_pk_bf16_f32 v174, v176, v177
	v_cvt_pk_bf16_f32 v175, v178, v179
	buffer_store_dwordx4 v[172:175], v37, s[84:87], 0 offen offset:1024 sc1
	v_cvt_pk_bf16_f32 v180, v180, v181
	v_cvt_pk_bf16_f32 v181, v182, v183
	v_cvt_pk_bf16_f32 v182, v184, v185
	v_cvt_pk_bf16_f32 v183, v186, v187
	buffer_store_dwordx4 v[180:183], v37, s[84:87], 0 offen offset:2048 sc1
	v_cvt_pk_bf16_f32 v188, v188, v189
	v_cvt_pk_bf16_f32 v189, v190, v191
	v_cvt_pk_bf16_f32 v190, v192, v193
	v_cvt_pk_bf16_f32 v191, v194, v195
	buffer_store_dwordx4 v[188:191], v37, s[84:87], 0 offen offset:3072 sc1
	v_add_u32_e32 v36, 0x2000, v36
	v_add_u32_e32 v37, 0x2000, v37
	global_load_dwordx4 v[132:135], v[2:3], off offset:-4096
	global_load_dwordx4 v[136:139], v[2:3], off offset:-4080
	global_load_dwordx4 v[140:143], v[2:3], off offset:-2048
	global_load_dwordx4 v[144:147], v[2:3], off offset:-2032
	global_load_dwordx4 v[148:151], v[2:3], off
	global_load_dwordx4 v[152:155], v[2:3], off offset:16
	global_load_dwordx4 v[156:159], v[2:3], off offset:2048
	global_load_dwordx4 v[160:163], v[2:3], off offset:2064
	global_load_dwordx4 v[164:167], v[4:5], off offset:-4096
	global_load_dwordx4 v[168:171], v[4:5], off offset:-4080
	global_load_dwordx4 v[172:175], v[4:5], off offset:-2048
	global_load_dwordx4 v[176:179], v[4:5], off offset:-2032
	global_load_dwordx4 v[180:183], v[4:5], off
	global_load_dwordx4 v[184:187], v[4:5], off offset:16
	global_load_dwordx4 v[188:191], v[4:5], off offset:2048
	global_load_dwordx4 v[192:195], v[4:5], off offset:2064
	v_lshl_add_u64 v[2:3], v[2:3], 0, s[10:11]
	v_lshl_add_u64 v[4:5], v[4:5], 0, s[10:11]
	s_waitcnt vmcnt(24)
	v_cvt_pk_bf16_f32 v68, v68, v69
	v_cvt_pk_bf16_f32 v69, v70, v71
	v_cvt_pk_bf16_f32 v70, v72, v73
	v_cvt_pk_bf16_f32 v71, v74, v75
	buffer_store_dwordx4 v[68:71], v36, s[84:87], 0 offen sc1
	v_cvt_pk_bf16_f32 v76, v76, v77
	v_cvt_pk_bf16_f32 v77, v78, v79
	v_cvt_pk_bf16_f32 v78, v80, v81
	v_cvt_pk_bf16_f32 v79, v82, v83
	buffer_store_dwordx4 v[76:79], v36, s[84:87], 0 offen offset:1024 sc1
	v_cvt_pk_bf16_f32 v84, v84, v85
	v_cvt_pk_bf16_f32 v85, v86, v87
	v_cvt_pk_bf16_f32 v86, v88, v89
	v_cvt_pk_bf16_f32 v87, v90, v91
	buffer_store_dwordx4 v[84:87], v36, s[84:87], 0 offen offset:2048 sc1
	v_cvt_pk_bf16_f32 v92, v92, v93
	v_cvt_pk_bf16_f32 v93, v94, v95
	v_cvt_pk_bf16_f32 v94, v96, v97
	v_cvt_pk_bf16_f32 v95, v98, v99
	buffer_store_dwordx4 v[92:95], v36, s[84:87], 0 offen offset:3072 sc1
	v_cvt_pk_bf16_f32 v100, v100, v101
	v_cvt_pk_bf16_f32 v101, v102, v103
	v_cvt_pk_bf16_f32 v102, v104, v105
	v_cvt_pk_bf16_f32 v103, v106, v107
	buffer_store_dwordx4 v[100:103], v37, s[84:87], 0 offen sc1
	v_cvt_pk_bf16_f32 v108, v108, v109
	v_cvt_pk_bf16_f32 v109, v110, v111
	v_cvt_pk_bf16_f32 v110, v112, v113
	v_cvt_pk_bf16_f32 v111, v114, v115
	buffer_store_dwordx4 v[108:111], v37, s[84:87], 0 offen offset:1024 sc1
	v_cvt_pk_bf16_f32 v116, v116, v117
	v_cvt_pk_bf16_f32 v117, v118, v119
	v_cvt_pk_bf16_f32 v118, v120, v121
	v_cvt_pk_bf16_f32 v119, v122, v123
	buffer_store_dwordx4 v[116:119], v37, s[84:87], 0 offen offset:2048 sc1
	v_cvt_pk_bf16_f32 v124, v124, v125
	v_cvt_pk_bf16_f32 v125, v126, v127
	v_cvt_pk_bf16_f32 v126, v128, v129
	v_cvt_pk_bf16_f32 v127, v130, v131
	buffer_store_dwordx4 v[124:127], v37, s[84:87], 0 offen offset:3072 sc1
	v_add_u32_e32 v36, 0x2000, v36
	v_add_u32_e32 v37, 0x2000, v37
	global_load_dwordx4 v[68:71], v[2:3], off offset:-4096
	global_load_dwordx4 v[72:75], v[2:3], off offset:-4080
	global_load_dwordx4 v[76:79], v[2:3], off offset:-2048
	global_load_dwordx4 v[80:83], v[2:3], off offset:-2032
	global_load_dwordx4 v[84:87], v[2:3], off
	global_load_dwordx4 v[88:91], v[2:3], off offset:16
	global_load_dwordx4 v[92:95], v[2:3], off offset:2048
	global_load_dwordx4 v[96:99], v[2:3], off offset:2064
	global_load_dwordx4 v[100:103], v[4:5], off offset:-4096
	global_load_dwordx4 v[104:107], v[4:5], off offset:-4080
	global_load_dwordx4 v[108:111], v[4:5], off offset:-2048
	global_load_dwordx4 v[112:115], v[4:5], off offset:-2032
	global_load_dwordx4 v[116:119], v[4:5], off
	global_load_dwordx4 v[120:123], v[4:5], off offset:16
	global_load_dwordx4 v[124:127], v[4:5], off offset:2048
	global_load_dwordx4 v[128:131], v[4:5], off offset:2064
	v_lshl_add_u64 v[2:3], v[2:3], 0, s[10:11]
	v_lshl_add_u64 v[4:5], v[4:5], 0, s[10:11]
	s_waitcnt vmcnt(24)
	v_cvt_pk_bf16_f32 v132, v132, v133
	v_cvt_pk_bf16_f32 v133, v134, v135
	v_cvt_pk_bf16_f32 v134, v136, v137
	v_cvt_pk_bf16_f32 v135, v138, v139
	buffer_store_dwordx4 v[132:135], v36, s[84:87], 0 offen sc1
	v_cvt_pk_bf16_f32 v140, v140, v141
	v_cvt_pk_bf16_f32 v141, v142, v143
	v_cvt_pk_bf16_f32 v142, v144, v145
	v_cvt_pk_bf16_f32 v143, v146, v147
	buffer_store_dwordx4 v[140:143], v36, s[84:87], 0 offen offset:1024 sc1
	v_cvt_pk_bf16_f32 v148, v148, v149
	v_cvt_pk_bf16_f32 v149, v150, v151
	v_cvt_pk_bf16_f32 v150, v152, v153
	v_cvt_pk_bf16_f32 v151, v154, v155
	buffer_store_dwordx4 v[148:151], v36, s[84:87], 0 offen offset:2048 sc1
	v_cvt_pk_bf16_f32 v156, v156, v157
	v_cvt_pk_bf16_f32 v157, v158, v159
	v_cvt_pk_bf16_f32 v158, v160, v161
	v_cvt_pk_bf16_f32 v159, v162, v163
	buffer_store_dwordx4 v[156:159], v36, s[84:87], 0 offen offset:3072 sc1
	v_cvt_pk_bf16_f32 v164, v164, v165
	v_cvt_pk_bf16_f32 v165, v166, v167
	v_cvt_pk_bf16_f32 v166, v168, v169
	v_cvt_pk_bf16_f32 v167, v170, v171
	buffer_store_dwordx4 v[164:167], v37, s[84:87], 0 offen sc1
	v_cvt_pk_bf16_f32 v172, v172, v173
	v_cvt_pk_bf16_f32 v173, v174, v175
	v_cvt_pk_bf16_f32 v174, v176, v177
	v_cvt_pk_bf16_f32 v175, v178, v179
	buffer_store_dwordx4 v[172:175], v37, s[84:87], 0 offen offset:1024 sc1
	v_cvt_pk_bf16_f32 v180, v180, v181
	v_cvt_pk_bf16_f32 v181, v182, v183
	v_cvt_pk_bf16_f32 v182, v184, v185
	v_cvt_pk_bf16_f32 v183, v186, v187
	buffer_store_dwordx4 v[180:183], v37, s[84:87], 0 offen offset:2048 sc1
	v_cvt_pk_bf16_f32 v188, v188, v189
	v_cvt_pk_bf16_f32 v189, v190, v191
	v_cvt_pk_bf16_f32 v190, v192, v193
	v_cvt_pk_bf16_f32 v191, v194, v195
	buffer_store_dwordx4 v[188:191], v37, s[84:87], 0 offen offset:3072 sc1
	v_add_u32_e32 v36, 0x2000, v36
	v_add_u32_e32 v37, 0x2000, v37
	global_load_dwordx4 v[132:135], v[2:3], off offset:-4096
	global_load_dwordx4 v[136:139], v[2:3], off offset:-4080
	global_load_dwordx4 v[140:143], v[2:3], off offset:-2048
	global_load_dwordx4 v[144:147], v[2:3], off offset:-2032
	global_load_dwordx4 v[148:151], v[2:3], off
	global_load_dwordx4 v[152:155], v[2:3], off offset:16
	global_load_dwordx4 v[156:159], v[2:3], off offset:2048
	global_load_dwordx4 v[160:163], v[2:3], off offset:2064
	global_load_dwordx4 v[164:167], v[4:5], off offset:-4096
	global_load_dwordx4 v[168:171], v[4:5], off offset:-4080
	global_load_dwordx4 v[172:175], v[4:5], off offset:-2048
	global_load_dwordx4 v[176:179], v[4:5], off offset:-2032
	global_load_dwordx4 v[180:183], v[4:5], off
	global_load_dwordx4 v[184:187], v[4:5], off offset:16
	global_load_dwordx4 v[188:191], v[4:5], off offset:2048
	global_load_dwordx4 v[192:195], v[4:5], off offset:2064
	v_lshl_add_u64 v[2:3], v[2:3], 0, s[10:11]
	v_lshl_add_u64 v[4:5], v[4:5], 0, s[10:11]
	s_waitcnt vmcnt(24)
	v_cvt_pk_bf16_f32 v68, v68, v69
	v_cvt_pk_bf16_f32 v69, v70, v71
	v_cvt_pk_bf16_f32 v70, v72, v73
	v_cvt_pk_bf16_f32 v71, v74, v75
	buffer_store_dwordx4 v[68:71], v36, s[84:87], 0 offen sc1
	v_cvt_pk_bf16_f32 v76, v76, v77
	v_cvt_pk_bf16_f32 v77, v78, v79
	v_cvt_pk_bf16_f32 v78, v80, v81
	v_cvt_pk_bf16_f32 v79, v82, v83
	buffer_store_dwordx4 v[76:79], v36, s[84:87], 0 offen offset:1024 sc1
	v_cvt_pk_bf16_f32 v84, v84, v85
	v_cvt_pk_bf16_f32 v85, v86, v87
	v_cvt_pk_bf16_f32 v86, v88, v89
	v_cvt_pk_bf16_f32 v87, v90, v91
	buffer_store_dwordx4 v[84:87], v36, s[84:87], 0 offen offset:2048 sc1
	v_cvt_pk_bf16_f32 v92, v92, v93
	v_cvt_pk_bf16_f32 v93, v94, v95
	v_cvt_pk_bf16_f32 v94, v96, v97
	v_cvt_pk_bf16_f32 v95, v98, v99
	buffer_store_dwordx4 v[92:95], v36, s[84:87], 0 offen offset:3072 sc1
	v_cvt_pk_bf16_f32 v100, v100, v101
	v_cvt_pk_bf16_f32 v101, v102, v103
	v_cvt_pk_bf16_f32 v102, v104, v105
	v_cvt_pk_bf16_f32 v103, v106, v107
	buffer_store_dwordx4 v[100:103], v37, s[84:87], 0 offen sc1
	v_cvt_pk_bf16_f32 v108, v108, v109
	v_cvt_pk_bf16_f32 v109, v110, v111
	v_cvt_pk_bf16_f32 v110, v112, v113
	v_cvt_pk_bf16_f32 v111, v114, v115
	buffer_store_dwordx4 v[108:111], v37, s[84:87], 0 offen offset:1024 sc1
	v_cvt_pk_bf16_f32 v116, v116, v117
	v_cvt_pk_bf16_f32 v117, v118, v119
	v_cvt_pk_bf16_f32 v118, v120, v121
	v_cvt_pk_bf16_f32 v119, v122, v123
	buffer_store_dwordx4 v[116:119], v37, s[84:87], 0 offen offset:2048 sc1
	v_cvt_pk_bf16_f32 v124, v124, v125
	v_cvt_pk_bf16_f32 v125, v126, v127
	v_cvt_pk_bf16_f32 v126, v128, v129
	v_cvt_pk_bf16_f32 v127, v130, v131
	buffer_store_dwordx4 v[124:127], v37, s[84:87], 0 offen offset:3072 sc1
	v_add_u32_e32 v36, 0x2000, v36
	v_add_u32_e32 v37, 0x2000, v37
	s_waitcnt vmcnt(8)
	v_cvt_pk_bf16_f32 v132, v132, v133
	v_cvt_pk_bf16_f32 v133, v134, v135
	v_cvt_pk_bf16_f32 v134, v136, v137
	v_cvt_pk_bf16_f32 v135, v138, v139
	buffer_store_dwordx4 v[132:135], v36, s[84:87], 0 offen sc1
	v_cvt_pk_bf16_f32 v140, v140, v141
	v_cvt_pk_bf16_f32 v141, v142, v143
	v_cvt_pk_bf16_f32 v142, v144, v145
	v_cvt_pk_bf16_f32 v143, v146, v147
	buffer_store_dwordx4 v[140:143], v36, s[84:87], 0 offen offset:1024 sc1
	v_cvt_pk_bf16_f32 v148, v148, v149
	v_cvt_pk_bf16_f32 v149, v150, v151
	v_cvt_pk_bf16_f32 v150, v152, v153
	v_cvt_pk_bf16_f32 v151, v154, v155
	buffer_store_dwordx4 v[148:151], v36, s[84:87], 0 offen offset:2048 sc1
	v_cvt_pk_bf16_f32 v156, v156, v157
	v_cvt_pk_bf16_f32 v157, v158, v159
	v_cvt_pk_bf16_f32 v158, v160, v161
	v_cvt_pk_bf16_f32 v159, v162, v163
	buffer_store_dwordx4 v[156:159], v36, s[84:87], 0 offen offset:3072 sc1
	v_cvt_pk_bf16_f32 v164, v164, v165
	v_cvt_pk_bf16_f32 v165, v166, v167
	v_cvt_pk_bf16_f32 v166, v168, v169
	v_cvt_pk_bf16_f32 v167, v170, v171
	buffer_store_dwordx4 v[164:167], v37, s[84:87], 0 offen sc1
	v_cvt_pk_bf16_f32 v172, v172, v173
	v_cvt_pk_bf16_f32 v173, v174, v175
	v_cvt_pk_bf16_f32 v174, v176, v177
	v_cvt_pk_bf16_f32 v175, v178, v179
	buffer_store_dwordx4 v[172:175], v37, s[84:87], 0 offen offset:1024 sc1
	v_cvt_pk_bf16_f32 v180, v180, v181
	v_cvt_pk_bf16_f32 v181, v182, v183
	v_cvt_pk_bf16_f32 v182, v184, v185
	v_cvt_pk_bf16_f32 v183, v186, v187
	buffer_store_dwordx4 v[180:183], v37, s[84:87], 0 offen offset:2048 sc1
	v_cvt_pk_bf16_f32 v188, v188, v189
	v_cvt_pk_bf16_f32 v189, v190, v191
	v_cvt_pk_bf16_f32 v190, v192, v193
	v_cvt_pk_bf16_f32 v191, v194, v195
	buffer_store_dwordx4 v[188:191], v37, s[84:87], 0 offen offset:3072 sc1
	v_add_u32_e32 v36, 0x2000, v36
	v_add_u32_e32 v37, 0x2000, v37
	s_waitcnt vmcnt(0)
	s_barrier
	s_mov_b64 s[38:39], exec
	v_readlane_b32 s10, v255, 23
	v_readlane_b32 s11, v255, 24
	s_and_b64 s[10:11], s[38:39], s[10:11]
	s_mov_b64 exec, s[10:11]
	s_cbranch_execz .LBB0_856
	s_mov_b64 s[40:41], exec
	v_mbcnt_lo_u32_b32 v2, s40, 0
	v_mbcnt_hi_u32_b32 v2, s41, v2
	v_cmp_eq_u32_e32 vcc, 0, v2
	s_and_b64 s[10:11], exec, vcc
	s_mov_b64 exec, s[10:11]
	s_cbranch_execz .LBB0_856
	s_and_b32 s9, s7, 0xf0
	s_lshl_b32 s9, s9, 2
	s_bcnt1_i32_b64 s10, s[40:41]
	v_mov_b32_e32 v2, s9
	v_mov_b32_e32 v3, s10
	global_atomic_add v2, v3, s[2:3] offset:1024
